# prologue fence v2: wave-0 write-back kept, redundant leader write-back inside the cooperative sync and the pre-sync invalidate removed
# speedup vs baseline: 1.0366x; 1.0039x over previous
; __global__ void __launch_bounds__(NTHREADS, 2) fwd_megakernel(Params P) {
;     ...
;     __threadfence();
;     __syncthreads();
;     grid.sync();
.Lpro_nofence:
	s_barrier
	s_and_saveexec_b64 s[0:1], vcc
	v_readlane_b32 s16, v250, 0
	v_readlane_b32 s18, v250, 2
	v_readlane_b32 s19, v250, 3
	v_readlane_b32 s17, v250, 1
	s_cbranch_execz .LBB0_94
	s_load_dwordx2 s[4:5], s[34:35], 0x58
	v_mov_b32_e32 v2, 0
	s_mov_b64 s[6:7], exec
	v_mbcnt_lo_u32_b32 v1, s6, 0
	v_mbcnt_hi_u32_b32 v1, s7, v1
	s_waitcnt lgkmcnt(0)
	global_load_dword v0, v2, s[4:5] offset:40
	v_cmp_eq_u32_e32 vcc, 0, v1
	s_and_saveexec_b64 s[8:9], vcc
	s_cbranch_execz .LBB0_87
	s_bcnt1_i32_b64 s6, s[6:7]
	v_mov_b32_e32 v3, s6
	global_atomic_add v3, v2, v3, s[4:5] offset:32 sc0
